# v7: attention->out-proj seam replaced by per-panel readiness counters (dataflow hand-off)
# speedup vs baseline: 1.0413x; 1.0029x over previous
; __device__ __forceinline__ int opaque_tid(int wv) { unsigned z = 0u; asm volatile("" : "+v"(z)); return (wv << 6) | (int)__builtin_amdgcn_mbcnt_hi(~0u, __builtin_amdgcn_mbcnt_lo(~0u, z)); }
; __global__ void __launch_bounds__(512) fwd_megakernel(Args A) {
;     ...
;             for (int ui_ = 0;; ++ui_) {
;                 int idx;
;                 if (ATT_DYNQ) {
;                     if (ui_ == 0) idx = bx;
;                     else {
;                         if (opaque_tid(wv) == 0) *qslot = G + (int)atomicAdd(ctr, 1u);
;                         __syncthreads();
;                         idx = *qslot;
;                         __syncthreads();
;                     }
;                 } else {
;                     idx = (ui_ == 1) ? (511 - bx) : (ui_ * 256 + bx);
;                     if (ui_ >= 3 || G != 256) idx = 768;
;                 }
;                 if (idx >= 768) break;
;                 const int code = att_code(idx >> 5), bh = idx & 31, type = code >> 3, qb = code & 7, bb = bh >> 3, h = bh & 7;
;                 if (type == 0) attn_unit<0>(bb, h, qb, (const bf16_t*)(ws + WS_QM), (const bf16_t*)(ws + WS_KN), (const bf16_t*)(ws + WS_KR), (const bf16_t*)(ws + WS_VTM), nullptr, gout, (bf16_t*)(ws + WS_OB), lds, wv);
;                 else if (type == 1) attn_unit<1>(bb, h, qb, QK4, QK4 + QS, nullptr, (const bf16_t*)(ws + WS_VTS), nullptr, gout, (bf16_t*)(ws + WS_OB), lds, wv);
;                 else attn_unit<2>(bb, h, qb, QK4 + 2 * QS, QK4 + 3 * QS, nullptr, (const bf16_t*)(ws + WS_VTS) + (size_t)512 * MTOK, (const float*)(ws + WS_NF2), gout, (bf16_t*)(ws + WS_OB), lds, wv);
;             }
.LBB0_529:
	s_or_b64 exec, exec, s[2:3]
	s_add_i32 s0, 0, 0x20000
	v_mov_b32_e32 v0, s0
	s_waitcnt vmcnt(0) lgkmcnt(0)
	s_barrier
	s_cmp_lg_u32 s94, 0
	s_cbranch_scc1 .Lpc_skip
	s_mov_b64 s[2:3], exec
	s_mov_b64 exec, 1
	v_readlane_b32 s4, v255, 8
	v_readlane_b32 s6, v251, 45
	v_readlane_b32 s7, v251, 46
	v_mov_b32_e32 v2, 1
	v_mov_b32_e32 v3, 0
	s_lshl_b32 s4, s4, 6
	s_add_u32 s4, s4, 0x7000
	s_add_u32 s4, s6, s4
	s_addc_u32 s5, s7, 0
	s_add_u32 s6, s6, 0x7800
	s_addc_u32 s7, s7, 0
	global_atomic_add v3, v2, s[4:5]
	global_atomic_add v3, v2, s[6:7]
	s_mov_b64 exec, s[2:3]
.Lpc_skip:
	ds_read_b32 v0, v0
	s_waitcnt lgkmcnt(0)
	s_barrier
	v_readfirstlane_b32 s1, v0
.LBB0_530:
	s_cmpk_gt_i32 s1, 0x2ff
	s_mov_b64 s[2:3], -1
	s_cbranch_scc1 .LBB0_523
	s_ashr_i32 s0, s1, 5
	s_add_i32 s4, s0, -12
	s_cmp_lt_i32 s0, 12
	s_mov_b32 s2, 0xab2c36d
	s_cselect_b32 s3, s2, 0x820114c
	s_mov_b32 s2, 0xc8e794c7
	s_cselect_b32 s0, s0, s4
	s_cselect_b32 s2, s2, 0x82a9d162
	s_mul_i32 s0, s0, 5
	s_lshr_b64 s[2:3], s[2:3], s0
	v_writelane_b32 v254, s8, 59
	s_and_b32 s3, s2, 24
	s_and_b32 s0, s2, 7
	s_bfe_u32 s95, s1, 0x20003
	s_and_b32 s33, s1, 7
	s_lshl_b32 s4, s95, 3
	s_add_i32 s4, s4, s0
	v_writelane_b32 v255, s4, 8
	s_mov_b64 s[6:7], -1
	v_writelane_b32 v254, s3, 60
	s_cmp_lt_i32 s3, 8
	s_mov_b64 s[4:5], 0
	s_cbranch_scc0 .LBB0_535
	s_and_b64 vcc, exec, s[6:7]
	s_mov_b64 s[2:3], 0
	s_cbranch_vccnz .LBB0_649

;     __device__ __forceinline__ void init(int M0, int N0, int c0, int M1, int N1, int c1, int G) { s0.init(M0, N0, G, c0); s1.init(M1, N1, G, c1); n0 = (c0 < s0.nwg) ? (s0.nwg - c0 + G - 1) / G : 0; }
; #define SEAM(k) do { } while (0)
; #define SEAM(k) do { if (lo <= (k) && (k) + 1 < hi) { if (hi > 1000) grid.sync(); else xcd_barrier(xbar, xst, opaque_tid(wv) == 0); } } while (0)
; __global__ void __launch_bounds__(512) fwd_megakernel(Args A) {
;     ...
;             SEAM(P + 3);
;         }
;         if (EN(5) && IN(P + 4)) {
;             pg8::Gemm g{(const bf16_t*)(ws + WS_OB), (const bf16_t*)(ws + WS_WOUT) + (size_t)l * DM * DM, MTOK, DM, DM}; pg8::StaticOrder S; S.init(MTOK, DM, G, bx);
;             EpiResNorm E{Xin, Xb, modl + 2 * DM, A.norm_ffn + l * DM, modl + 3 * DM, modl + 4 * DM, Hb, nullptr, 0,
;                          (float*)(ws + WS_XCH) + (size_t)(2 * l) * MTOK * 8, (unsigned*)(ws + WS_CTL) + 8192 + (2 * l) * 2048, (unsigned*)(ws + WS_CTL) + 2};
;             pg8::gemm_phase(lds, g, S, E, wv);
.LBB0_684:
	v_readlane_b32 s0, v254, 45
	v_readlane_b32 s4, v251, 41
	s_or_b32 s0, s0, 5
	v_readlane_b32 s11, v251, 48
	s_cmp_ge_i32 s0, s11
	v_readlane_b32 s1, v254, 46
	v_readlane_b32 s5, v251, 42
	v_readlane_b32 s6, v251, 43
	v_readlane_b32 s7, v251, 44
	v_readlane_b32 s8, v251, 45
	v_readlane_b32 s9, v251, 46
	v_readlane_b32 s10, v251, 47
	s_cbranch_scc1 .LBB0_751
	v_readlane_b32 s4, v252, 13
	v_readlane_b32 s5, v252, 14
	s_mov_b64 s[2:3], -1
	s_and_b64 vcc, exec, s[4:5]
	s_cbranch_vccz .LBB0_739
	s_cmp_eq_u32 s100, 0
	s_cbranch_scc1 .Lpw_orig
	s_waitcnt vmcnt(0) lgkmcnt(0)
	s_barrier
	s_cmp_lg_u32 s94, 0
	s_cbranch_scc1 .Lpw_join
	s_mov_b64 exec, 1
	v_readlane_b32 s8, v251, 45
	v_readlane_b32 s9, v251, 46
	v_readlane_b32 s6, v251, 50
	v_readlane_b32 s12, v254, 57
	v_mov_b32_e32 v8, 0
	s_and_b32 s10, s6, 7
	s_lshl_b32 s10, s10, 2
	s_bfe_u32 s11, s6, 0x20003
	s_add_u32 s10, s10, s11
	s_lshl_b32 s10, s10, 6
	s_add_u32 s10, s10, 0x7000
	s_add_u32 s8, s8, s10
	s_addc_u32 s9, s9, 0
	s_add_u32 s12, s12, 1
	s_mul_i32 s13, s12, 24
	s_mov_b32 s16, 0
.Lpw_w:
	global_load_dword v6, v8, s[8:9] sc1
	s_add_u32 s16, s16, 1
	s_waitcnt vmcnt(0)
	v_readfirstlane_b32 s15, v6
	s_cmp_ge_u32 s15, s13
	s_cbranch_scc1 .Lpw_done
	s_sleep 1
	s_cmp_lt_u32 s16, 0x400000
	s_cbranch_scc1 .Lpw_w

; #define LAS __attribute__((address_space(3)))
; __device__ __forceinline__ unsigned xb_add(unsigned* p, unsigned v) { return __hip_atomic_fetch_add(p, v, __ATOMIC_RELAXED, __HIP_MEMORY_SCOPE_AGENT); }
; __device__ __forceinline__ unsigned xb_xcc_id() { return (unsigned)__builtin_amdgcn_s_getreg((3 << 11) | 20) & 0xFu; }
; __device__ __forceinline__ void xcd_barrier(unsigned* bar, volatile LAS unsigned* st, bool is0) {
;     asm volatile("s_waitcnt vmcnt(0)" ::: "memory");
;     __syncthreads();
;     if (is0) {
;         __builtin_amdgcn_s_waitcnt(0);
;         const unsigned x = xb_xcc_id();
;         unsigned nloc = st[0], nx = st[1];
;         if (nloc == 0u) { xcd_barrier_complete(bar, x, nloc, nx); st[0] = nloc; st[1] = nx; }
;         const unsigned old = xb_add(&bar[XB_XSUB(x)], 1u);
.Lpw_join:
	s_mov_b64 s[2:3], 0
	s_barrier
	s_branch .Lpw_after
.Lpw_orig:
	v_mov_b32_e32 v0, v1
	s_waitcnt vmcnt(0)
	s_waitcnt vmcnt(0) lgkmcnt(0)
	v_mbcnt_lo_u32_b32 v0, -1, v0
	v_mbcnt_hi_u32_b32 v0, -1, v0
	v_or_b32_e32 v0, s94, v0
	v_cmp_eq_u32_e32 vcc, 0, v0
	s_barrier
	s_and_saveexec_b64 s[2:3], vcc
	s_cbranch_execz .LBB0_738
	v_readlane_b32 s4, v254, 35
	s_waitcnt vmcnt(0) expcnt(0) lgkmcnt(0)
	s_getreg_b32 s1, hwreg(HW_REG_XCC_ID, 0, 4)
	v_mov_b32_e32 v0, s4
	ds_read_b32 v3, v0
	v_readlane_b32 s4, v254, 36
	s_and_b32 s1, s1, 15
	s_waitcnt lgkmcnt(0)
	v_cmp_ne_u32_e32 vcc, 0, v3
	v_mov_b32_e32 v0, s4
	ds_read_b32 v2, v0
	s_cbranch_vccnz .LBB0_702
	s_mov_b32 s10, 1
	s_branch .LBB0_690

; #define LAS __attribute__((address_space(3)))
; __device__ __forceinline__ int opaque_tid(int wv) { unsigned z = 0u; asm volatile("" : "+v"(z)); return (wv << 6) | (int)__builtin_amdgcn_mbcnt_hi(~0u, __builtin_amdgcn_mbcnt_lo(~0u, z)); }
; __device__ __forceinline__ unsigned xb_ld(unsigned* p)              { return __hip_atomic_load(p, __ATOMIC_RELAXED, __HIP_MEMORY_SCOPE_AGENT); }
; __device__ __forceinline__ unsigned xb_add(unsigned* p, unsigned v) { return __hip_atomic_fetch_add(p, v, __ATOMIC_RELAXED, __HIP_MEMORY_SCOPE_AGENT); }
; __device__ __forceinline__ void xcd_barrier(unsigned* bar, volatile LAS unsigned* st, bool is0) {
;     asm volatile("s_waitcnt vmcnt(0)" ::: "memory");
;     __syncthreads();
;     if (is0) {
;         __builtin_amdgcn_s_waitcnt(0);
;         const unsigned x = xb_xcc_id();
;         unsigned nloc = st[0], nx = st[1];
;         if (nloc == 0u) { xcd_barrier_complete(bar, x, nloc, nx); st[0] = nloc; st[1] = nx; }
;         const unsigned old = xb_add(&bar[XB_XSUB(x)], 1u);
;         const unsigned gen = old / nloc;
;         if (old + 1u == (gen + 1u) * nloc) {
;             __builtin_amdgcn_fence(__ATOMIC_RELEASE, "agent");
;             asm volatile("s_waitcnt vmcnt(0)" ::: "memory");
;             const unsigned og = xb_add(&bar[XB_TOP], 1u);
;             const unsigned tg = og / nx;
;             if (og + 1u == (tg + 1u) * nx) xb_add(&bar[XB_TOPGEN], 1u);
;             else XB_SPIN(xb_ld(&bar[XB_TOPGEN]) == tg, bar);
;             __builtin_amdgcn_fence(__ATOMIC_ACQUIRE, "agent");
;             xb_add(&bar[XB_XGEN(x)], 1u);
;             asm volatile("s_waitcnt vmcnt(0)" ::: "memory");
;         } else {
;             XB_SPIN(xb_ld(&bar[XB_XGEN(x)]) == gen, bar);
;             __builtin_amdgcn_fence(__ATOMIC_ACQUIRE, "agent");
;             asm volatile("s_waitcnt vmcnt(0)" ::: "memory");
;         }
;     }
;     __syncthreads();
; }
; __global__ void __launch_bounds__(512) fwd_megakernel(Args A) {
;     ...
;     cg::grid_group grid = cg::this_grid();
;     unsigned* xbar = (unsigned*)(ws + WS_CTL) + 1024;
;     volatile LAS unsigned* xst = (volatile LAS unsigned*)(lds + MISC_OFF + 64);
;     { const int t0_ = opaque_tid(wv); if (t0_ == 0) { xst[0] = 0u; xst[1] = 0u; (void)xb_add(&xbar[XB_XCNT(xb_xcc_id())], 1u); } }
.Lpw_after:
.LBB0_739:
	s_and_b64 vcc, exec, s[2:3]
	s_cbranch_vccz .LBB0_751
	s_waitcnt vmcnt(0) lgkmcnt(0)
	s_barrier
	s_mov_b64 s[2:3], exec
	v_readlane_b32 s4, v254, 37
	v_readlane_b32 s5, v254, 38
	s_and_b64 s[4:5], s[2:3], s[4:5]
	s_mov_b64 exec, s[4:5]
	s_cbranch_execz .LBB0_750
	v_readlane_b32 s4, v251, 0
	v_readlane_b32 s5, v251, 1
	buffer_wbl2 sc1
	s_load_dwordx2 s[4:5], s[4:5], 0x58
	s_mov_b64 s[6:7], exec
	v_mbcnt_lo_u32_b32 v2, s6, 0
	v_mbcnt_hi_u32_b32 v2, s7, v2
	v_cmp_eq_u32_e32 vcc, 0, v2
	s_waitcnt lgkmcnt(0)
	global_load_dword v0, v1, s[4:5] offset:40
	s_and_saveexec_b64 s[8:9], vcc
	s_cbranch_execz .LBB0_743
	s_bcnt1_i32_b64 s1, s[6:7]
	v_mov_b32_e32 v3, s1
	global_atomic_add v3, v1, v3, s[4:5] offset:32 sc0

; #define LAS __attribute__((address_space(3)))
; __device__ __forceinline__ unsigned xb_ld(unsigned* p)              { return __hip_atomic_load(p, __ATOMIC_RELAXED, __HIP_MEMORY_SCOPE_AGENT); }
; __device__ __forceinline__ unsigned xb_add(unsigned* p, unsigned v) { return __hip_atomic_fetch_add(p, v, __ATOMIC_RELAXED, __HIP_MEMORY_SCOPE_AGENT); }
; __device__ __forceinline__ unsigned xb_xcc_id() { return (unsigned)__builtin_amdgcn_s_getreg((3 << 11) | 20) & 0xFu; }
; #define XB_SPIN(cond, bar) do { unsigned _sp = 0; while (cond) { __builtin_amdgcn_s_sleep(1); \
;     if ((++_sp & 255u) == 0u) { if (xb_ld(&(bar)[XB_TMO])) break; if (_sp > XB_SPIN_CAP) { atomicAdd(&(bar)[XB_TMO], 1u); break; } } } } while (0)
; #define SEAM(k) do { } while (0)
; __device__ __forceinline__ void xcd_barrier(unsigned* bar, volatile LAS unsigned* st, bool is0) {
;     asm volatile("s_waitcnt vmcnt(0)" ::: "memory");
;     __syncthreads();
;     if (is0) {
;         __builtin_amdgcn_s_waitcnt(0);
;         const unsigned x = xb_xcc_id();
;         unsigned nloc = st[0], nx = st[1];
;         if (nloc == 0u) { xcd_barrier_complete(bar, x, nloc, nx); st[0] = nloc; st[1] = nx; }
;         const unsigned old = xb_add(&bar[XB_XSUB(x)], 1u);
;         const unsigned gen = old / nloc;
;         if (old + 1u == (gen + 1u) * nloc) {
;             __builtin_amdgcn_fence(__ATOMIC_RELEASE, "agent");
;             asm volatile("s_waitcnt vmcnt(0)" ::: "memory");
;             const unsigned og = xb_add(&bar[XB_TOP], 1u);
;             const unsigned tg = og / nx;
;             if (og + 1u == (tg + 1u) * nx) xb_add(&bar[XB_TOPGEN], 1u);
;             else XB_SPIN(xb_ld(&bar[XB_TOPGEN]) == tg, bar);
;             __builtin_amdgcn_fence(__ATOMIC_ACQUIRE, "agent");
;             xb_add(&bar[XB_XGEN(x)], 1u);
;             asm volatile("s_waitcnt vmcnt(0)" ::: "memory");
;         } else {
;             XB_SPIN(xb_ld(&bar[XB_XGEN(x)]) == gen, bar);
;             __builtin_amdgcn_fence(__ATOMIC_ACQUIRE, "agent");
;             asm volatile("s_waitcnt vmcnt(0)" ::: "memory");
;         }
;     }
;     __syncthreads();
; }
; __global__ void __launch_bounds__(512) fwd_megakernel(Args A) {
;     ...
;             pg8::gemm_phase(lds, g, S, E, wv);
;             SEAM(P + 7);
;         }
.LBB0_1242:
	v_readlane_b32 s0, v252, 13
	v_readlane_b32 s1, v252, 14
	s_mov_b64 s[2:3], -1
	s_and_b64 vcc, exec, s[0:1]
	s_cbranch_vccz .LBB0_1296
	s_cmp_eq_u32 s100, 0
	s_cbranch_scc1 .Lgb_orig_5
	s_waitcnt vmcnt(0) lgkmcnt(0)
	s_barrier
	s_cmp_lg_u32 s94, 0
	s_cbranch_scc1 .Lgb_join_5
	s_mov_b64 exec, 1
	v_readlane_b32 s8, v251, 45
	v_readlane_b32 s9, v251, 46
	v_readlane_b32 s6, v251, 50
	v_mov_b32_e32 v4, 1
	v_mov_b32_e32 v8, 0
	s_and_b32 s6, s6, 7
	s_lshl_b32 s6, s6, 8
	s_add_u32 s6, s6, 0x5000
	s_add_u32 s8, s8, s6
	s_addc_u32 s9, s9, 0
	v_readlane_b32 s18, v251, 45
	v_readlane_b32 s19, v251, 46
	v_readlane_b32 s12, v254, 57
	s_add_u32 s18, s18, 0x7800
	s_addc_u32 s19, s19, 0
	s_add_u32 s12, s12, 1
	s_mul_i32 s14, s12, 0x300
	s_mov_b32 s16, 0
.Ltot_w:
	global_load_dword v6, v8, s[18:19] sc1
	s_add_u32 s16, s16, 1
	s_waitcnt vmcnt(0)
	v_readfirstlane_b32 s15, v6
	s_cmp_ge_u32 s15, s14
	s_cbranch_scc1 .Ltot_done
	s_sleep 1
	s_cmp_lt_u32 s16, 0x400000
	s_cbranch_scc1 .Ltot_w
.Ltot_done:
	s_add_u32 s12, s101, 1
	s_lshl_b32 s13, s12, 5
	s_cmp_eq_u32 s100, 2
	s_cbranch_scc1 .Lgb_arr_5
	buffer_wbl2 sc1
	s_waitcnt vmcnt(0)
